# attention finalize output stores: half-sector dwordx4 (32 rows x 32 B) -> full-sector (16 rows x 64 B) via v_permlane16_swap of quad pairs; second store 16 rows further
# speedup vs baseline: 1.0053x; 1.0053x over previous
; DI void dattn_unit2(const bf16_t* __restrict__ Qg, const bf16_t* __restrict__ Kg, const bf16_t* __restrict__ Vg, bf16_t* __restrict__ Og,
;                     int ntiles, int wave_tiles, float lam, const float* __restrict__ gsub, lds_t* shm) {
;     ...
;   const float l0 = lrun[0] + __shfl_xor(lrun[0], 32), l1 = lrun[1] + __shfl_xor(lrun[1], 32);
;   const float i0 = 1.0f / l0, i1 = lam / l1;
;   float ssq = 0.f;
; #pragma unroll
;   for (int c = 0; c < NC; ++c)
; #pragma unroll
;     for (int i = 0; i < 16; ++i) { const float a = O[0][c][i] * i0 - O[1][c][i] * i1; O[0][c][i] = a; ssq += a * a; }
.LBB0_414:
	ds_bpermute_b32 v128, v213, v201
	ds_bpermute_b32 v129, v213, v200
	s_lshl_b64 s[4:5], s[42:43], 1
	s_add_u32 s4, s35, s4
	s_addc_u32 s5, s46, s5
	s_waitcnt lgkmcnt(0)
	v_add_f32_e32 v128, v201, v128
	v_div_scale_f32 v130, s[6:7], v128, v128, 1.0
	v_rcp_f32_e32 v131, v130
	v_add_f32_e32 v129, v200, v129
	v_fma_f32 v132, -v130, v131, 1.0
	v_fmac_f32_e32 v131, v132, v131
	v_div_scale_f32 v132, vcc, 1.0, v128, 1.0
	v_mul_f32_e32 v133, v132, v131
	v_fma_f32 v134, -v130, v133, v132
	v_fmac_f32_e32 v133, v134, v131
	v_fma_f32 v130, -v130, v133, v132
	v_div_scale_f32 v132, s[6:7], v129, v129, v215
	v_rcp_f32_e32 v134, v132
	v_div_fmas_f32 v130, v130, v131, v133
	v_div_fixup_f32 v138, v130, v128, 1.0
	v_fma_f32 v128, -v132, v134, 1.0
	v_fmac_f32_e32 v134, v128, v134
	v_div_scale_f32 v128, vcc, v215, v129, v215
	v_mul_f32_e32 v130, v128, v134
	v_fma_f32 v131, -v132, v130, v128
	v_fmac_f32_e32 v130, v131, v134
	v_fma_f32 v128, -v132, v130, v128
	v_div_fmas_f32 v128, v128, v134, v130
	v_div_fixup_f32 v140, v128, v129, v215
	v_pk_mul_f32 v[28:29], v[28:29], v[140:141] op_sel_hi:[1,0]
	s_nop 0
	v_pk_fma_f32 v[128:129], v[12:13], v[138:139], v[28:29] op_sel_hi:[1,0,1] neg_lo:[0,0,1] neg_hi:[0,0,1]
	v_pk_mul_f32 v[12:13], v[30:31], v[140:141] op_sel_hi:[1,0]
	v_pk_mul_f32 v[134:135], v[128:129], v[128:129]
	v_pk_fma_f32 v[130:131], v[14:15], v[138:139], v[12:13] op_sel_hi:[1,0,1] neg_lo:[0,0,1] neg_hi:[0,0,1]
	v_mov_b32_e32 v139, v212
	v_pk_mul_f32 v[136:137], v[130:131], v[130:131]
	v_bfe_u32 v141, v139, 5, 1
	v_pk_mul_f32 v[12:13], v[112:113], v[140:141] op_sel_hi:[1,0]
	v_pk_mul_f32 v[28:29], v[80:81], v[140:141] op_sel_hi:[1,0]
	v_pk_fma_f32 v[112:113], v[96:97], v[138:139], v[12:13] op_sel_hi:[1,0,1] neg_lo:[0,0,1] neg_hi:[0,0,1]
	v_pk_mul_f32 v[12:13], v[114:115], v[140:141] op_sel_hi:[1,0]
	v_pk_fma_f32 v[80:81], v[64:65], v[138:139], v[28:29] op_sel_hi:[1,0,1] neg_lo:[0,0,1] neg_hi:[0,0,1]
	v_pk_fma_f32 v[132:133], v[98:99], v[138:139], v[12:13] op_sel_hi:[1,0,1] neg_lo:[0,0,1] neg_hi:[0,0,1]
	v_pk_mul_f32 v[12:13], v[116:117], v[140:141] op_sel_hi:[1,0]
	v_pk_mul_f32 v[28:29], v[82:83], v[140:141] op_sel_hi:[1,0]
	v_pk_fma_f32 v[114:115], v[100:101], v[138:139], v[12:13] op_sel_hi:[1,0,1] neg_lo:[0,0,1] neg_hi:[0,0,1]
	v_pk_mul_f32 v[12:13], v[118:119], v[140:141] op_sel_hi:[1,0]
	v_pk_fma_f32 v[82:83], v[66:67], v[138:139], v[28:29] op_sel_hi:[1,0,1] neg_lo:[0,0,1] neg_hi:[0,0,1]
	v_pk_mul_f32 v[28:29], v[84:85], v[140:141] op_sel_hi:[1,0]
	v_pk_fma_f32 v[118:119], v[102:103], v[138:139], v[12:13] op_sel_hi:[1,0,1] neg_lo:[0,0,1] neg_hi:[0,0,1]
	v_pk_mul_f32 v[12:13], v[120:121], v[140:141] op_sel_hi:[1,0]
	v_pk_fma_f32 v[84:85], v[68:69], v[138:139], v[28:29] op_sel_hi:[1,0,1] neg_lo:[0,0,1] neg_hi:[0,0,1]
	v_pk_mul_f32 v[68:69], v[88:89], v[140:141] op_sel_hi:[1,0]
	v_pk_fma_f32 v[116:117], v[104:105], v[138:139], v[12:13] op_sel_hi:[1,0,1] neg_lo:[0,0,1] neg_hi:[0,0,1]
	v_pk_mul_f32 v[12:13], v[122:123], v[140:141] op_sel_hi:[1,0]
	v_pk_fma_f32 v[88:89], v[72:73], v[138:139], v[68:69] op_sel_hi:[1,0,1] neg_lo:[0,0,1] neg_hi:[0,0,1]
	v_pk_mul_f32 v[68:69], v[90:91], v[140:141] op_sel_hi:[1,0]
	v_pk_fma_f32 v[122:123], v[106:107], v[138:139], v[12:13] op_sel_hi:[1,0,1] neg_lo:[0,0,1] neg_hi:[0,0,1]
	v_pk_mul_f32 v[12:13], v[124:125], v[140:141] op_sel_hi:[1,0]
	v_pk_fma_f32 v[90:91], v[74:75], v[138:139], v[68:69] op_sel_hi:[1,0,1] neg_lo:[0,0,1] neg_hi:[0,0,1]
	v_pk_mul_f32 v[68:69], v[92:93], v[140:141] op_sel_hi:[1,0]
	v_pk_mul_f32 v[48:49], v[48:49], v[140:141] op_sel_hi:[1,0]
	v_pk_mul_f32 v[142:143], v[112:113], v[112:113]
	v_pk_fma_f32 v[120:121], v[108:109], v[138:139], v[12:13] op_sel_hi:[1,0,1] neg_lo:[0,0,1] neg_hi:[0,0,1]
	v_pk_mul_f32 v[12:13], v[126:127], v[140:141] op_sel_hi:[1,0]
	v_pk_mul_f32 v[28:29], v[86:87], v[140:141] op_sel_hi:[1,0]
	v_pk_fma_f32 v[76:77], v[76:77], v[138:139], v[68:69] op_sel_hi:[1,0,1] neg_lo:[0,0,1] neg_hi:[0,0,1]
	v_pk_mul_f32 v[68:69], v[94:95], v[140:141] op_sel_hi:[1,0]
	v_pk_fma_f32 v[48:49], v[32:33], v[138:139], v[48:49] op_sel_hi:[1,0,1] neg_lo:[0,0,1] neg_hi:[0,0,1]
	v_pk_mul_f32 v[32:33], v[50:51], v[140:141] op_sel_hi:[1,0]
	v_pk_mul_f32 v[52:53], v[52:53], v[140:141] op_sel_hi:[1,0]
	v_pk_mul_f32 v[54:55], v[54:55], v[140:141] op_sel_hi:[1,0]
	v_pk_mul_f32 v[56:57], v[56:57], v[140:141] op_sel_hi:[1,0]
	v_pk_mul_f32 v[58:59], v[58:59], v[140:141] op_sel_hi:[1,0]
	v_pk_mul_f32 v[60:61], v[60:61], v[140:141] op_sel_hi:[1,0]
	v_pk_mul_f32 v[62:63], v[62:63], v[140:141] op_sel_hi:[1,0]
	v_pk_mul_f32 v[16:17], v[16:17], v[140:141] op_sel_hi:[1,0]
	v_pk_mul_f32 v[18:19], v[18:19], v[140:141] op_sel_hi:[1,0]
	v_pk_mul_f32 v[20:21], v[20:21], v[140:141] op_sel_hi:[1,0]
	v_pk_mul_f32 v[22:23], v[22:23], v[140:141] op_sel_hi:[1,0]
	v_pk_mul_f32 v[24:25], v[24:25], v[140:141] op_sel_hi:[1,0]
	v_pk_mul_f32 v[26:27], v[26:27], v[140:141] op_sel_hi:[1,0]
	v_lshlrev_b32_e32 v168, 4, v141
	v_pk_mul_f32 v[144:145], v[132:133], v[132:133]
	v_pk_fma_f32 v[108:109], v[110:111], v[138:139], v[12:13] op_sel_hi:[1,0,1] neg_lo:[0,0,1] neg_hi:[0,0,1]
	v_pk_fma_f32 v[86:87], v[70:71], v[138:139], v[28:29] op_sel_hi:[1,0,1] neg_lo:[0,0,1] neg_hi:[0,0,1]
	v_pk_fma_f32 v[78:79], v[78:79], v[138:139], v[68:69] op_sel_hi:[1,0,1] neg_lo:[0,0,1] neg_hi:[0,0,1]
	v_pk_fma_f32 v[50:51], v[34:35], v[138:139], v[32:33] op_sel_hi:[1,0,1] neg_lo:[0,0,1] neg_hi:[0,0,1]
	v_pk_fma_f32 v[36:37], v[36:37], v[138:139], v[52:53] op_sel_hi:[1,0,1] neg_lo:[0,0,1] neg_hi:[0,0,1]
	v_pk_fma_f32 v[38:39], v[38:39], v[138:139], v[54:55] op_sel_hi:[1,0,1] neg_lo:[0,0,1] neg_hi:[0,0,1]
; DI int tidx() { int t = threadIdx.x; asm volatile("" : "+v"(t)); return t; }
; DI void dattn_unit2(const bf16_t* __restrict__ Qg, const bf16_t* __restrict__ Kg, const bf16_t* __restrict__ Vg, bf16_t* __restrict__ Og,
;                     int ntiles, int wave_tiles, float lam, const float* __restrict__ gsub, lds_t* shm) {
;     ...
;     for (int i = 0; i < 16; ++i) { const float a = O[0][c][i] * i0 - O[1][c][i] * i1; O[0][c][i] = a; ssq += a * a; }
;   ssq += __shfl_xor(ssq, 32);
;   const float inv = rsqrtf(ssq * (1.0f / 128.0f) + RMS_EPS) * 0.8f;
;   const int lane_f = tidx() & 63, h_f = lane_f >> 5;
;   const unsigned ooff = ((unsigned)(lane_f & 31) * (unsigned)LD + 4u * h_f) * 2u;
	v_pk_fma_f32 v[40:41], v[40:41], v[138:139], v[56:57] op_sel_hi:[1,0,1] neg_lo:[0,0,1] neg_hi:[0,0,1]
	v_pk_fma_f32 v[42:43], v[42:43], v[138:139], v[58:59] op_sel_hi:[1,0,1] neg_lo:[0,0,1] neg_hi:[0,0,1]
	v_pk_fma_f32 v[44:45], v[44:45], v[138:139], v[60:61] op_sel_hi:[1,0,1] neg_lo:[0,0,1] neg_hi:[0,0,1]
	v_pk_fma_f32 v[46:47], v[46:47], v[138:139], v[62:63] op_sel_hi:[1,0,1] neg_lo:[0,0,1] neg_hi:[0,0,1]
	v_pk_fma_f32 v[0:1], v[0:1], v[138:139], v[16:17] op_sel_hi:[1,0,1] neg_lo:[0,0,1] neg_hi:[0,0,1]
	v_pk_fma_f32 v[2:3], v[2:3], v[138:139], v[18:19] op_sel_hi:[1,0,1] neg_lo:[0,0,1] neg_hi:[0,0,1]
	v_pk_fma_f32 v[4:5], v[4:5], v[138:139], v[20:21] op_sel_hi:[1,0,1] neg_lo:[0,0,1] neg_hi:[0,0,1]
	v_pk_fma_f32 v[6:7], v[6:7], v[138:139], v[22:23] op_sel_hi:[1,0,1] neg_lo:[0,0,1] neg_hi:[0,0,1]
	v_pk_fma_f32 v[8:9], v[8:9], v[138:139], v[24:25] op_sel_hi:[1,0,1] neg_lo:[0,0,1] neg_hi:[0,0,1]
	v_pk_fma_f32 v[10:11], v[10:11], v[138:139], v[26:27] op_sel_hi:[1,0,1] neg_lo:[0,0,1] neg_hi:[0,0,1]
	v_add_f32_e32 v138, v142, v143
	global_load_dwordx4 v[100:103], v168, s[38:39]
	global_load_dwordx4 v[96:99], v168, s[38:39] offset:32
	v_add_f32_e32 v138, v144, v138
	v_pk_mul_f32 v[146:147], v[114:115], v[114:115]
	v_add_f32_e32 v138, v145, v138
	v_add_f32_e32 v138, v146, v138
	v_pk_mul_f32 v[148:149], v[118:119], v[118:119]
	v_add_f32_e32 v138, v147, v138
	v_add_f32_e32 v138, v148, v138
	v_pk_mul_f32 v[150:151], v[116:117], v[116:117]
	v_add_f32_e32 v138, v149, v138
	global_load_dwordx4 v[104:107], v168, s[38:39] offset:64
	global_load_dwordx4 v[12:15], v168, s[38:39] offset:96
	v_add_f32_e32 v138, v150, v138
	v_pk_mul_f32 v[152:153], v[122:123], v[122:123]
	v_add_f32_e32 v138, v151, v138
	v_add_f32_e32 v138, v152, v138
	v_pk_mul_f32 v[124:125], v[120:121], v[120:121]
	v_add_f32_e32 v138, v153, v138
	v_add_f32_e32 v124, v124, v138
	v_pk_mul_f32 v[110:111], v[108:109], v[108:109]
	v_add_f32_e32 v124, v125, v124
	v_add_f32_e32 v110, v110, v124
	v_pk_mul_f32 v[126:127], v[80:81], v[80:81]
	v_add_f32_e32 v110, v111, v110
	v_add_f32_e32 v110, v126, v110
	v_pk_mul_f32 v[154:155], v[82:83], v[82:83]
	v_add_f32_e32 v110, v127, v110
	v_add_f32_e32 v110, v154, v110
	v_pk_mul_f32 v[156:157], v[84:85], v[84:85]
	v_add_f32_e32 v110, v155, v110
	v_add_f32_e32 v110, v156, v110
	v_pk_mul_f32 v[158:159], v[86:87], v[86:87]
	v_add_f32_e32 v110, v157, v110
	v_add_f32_e32 v110, v158, v110
	v_pk_mul_f32 v[160:161], v[88:89], v[88:89]
	v_add_f32_e32 v110, v159, v110
	v_add_f32_e32 v110, v160, v110
	v_pk_mul_f32 v[162:163], v[90:91], v[90:91]
	v_add_f32_e32 v110, v161, v110
	v_add_f32_e32 v110, v162, v110
	v_pk_mul_f32 v[92:93], v[76:77], v[76:77]
	v_add_f32_e32 v110, v163, v110
	v_add_f32_e32 v92, v92, v110
	v_pk_mul_f32 v[94:95], v[78:79], v[78:79]
	v_add_f32_e32 v92, v93, v92
	v_add_f32_e32 v92, v94, v92
	v_pk_mul_f32 v[164:165], v[48:49], v[48:49]
	v_add_f32_e32 v92, v95, v92
	v_add_f32_e32 v92, v164, v92
	v_pk_mul_f32 v[166:167], v[50:51], v[50:51]
	v_add_f32_e32 v92, v165, v92
	v_add_f32_e32 v92, v166, v92
	v_pk_mul_f32 v[52:53], v[36:37], v[36:37]
	v_add_f32_e32 v92, v167, v92
	v_add_f32_e32 v52, v52, v92
	v_pk_mul_f32 v[54:55], v[38:39], v[38:39]
	v_add_f32_e32 v52, v53, v52
	v_add_f32_e32 v52, v54, v52
	v_pk_mul_f32 v[56:57], v[40:41], v[40:41]
	v_add_f32_e32 v52, v55, v52
	v_add_f32_e32 v52, v56, v52
	v_pk_mul_f32 v[58:59], v[42:43], v[42:43]
	v_add_f32_e32 v52, v57, v52
	v_add_f32_e32 v52, v58, v52
	v_pk_mul_f32 v[60:61], v[44:45], v[44:45]
	v_add_f32_e32 v52, v59, v52
	v_add_f32_e32 v52, v60, v52
	v_pk_mul_f32 v[62:63], v[46:47], v[46:47]
	v_add_f32_e32 v52, v61, v52
	v_add_f32_e32 v52, v62, v52
	v_pk_mul_f32 v[16:17], v[0:1], v[0:1]
	v_add_f32_e32 v52, v63, v52
	v_add_f32_e32 v16, v16, v52
	v_pk_mul_f32 v[18:19], v[2:3], v[2:3]
	v_add_f32_e32 v16, v17, v16
	v_add_f32_e32 v16, v18, v16
	v_pk_mul_f32 v[20:21], v[4:5], v[4:5]
	v_add_f32_e32 v16, v19, v16
	v_add_f32_e32 v16, v20, v16
	v_pk_mul_f32 v[22:23], v[6:7], v[6:7]
	v_add_f32_e32 v16, v21, v16
	v_add_f32_e32 v16, v22, v16
	v_pk_mul_f32 v[24:25], v[8:9], v[8:9]
	v_add_f32_e32 v16, v23, v16
	v_add_f32_e32 v16, v24, v16
	v_pk_mul_f32 v[26:27], v[10:11], v[10:11]
	v_add_f32_e32 v16, v25, v16
	v_add_f32_e32 v16, v26, v16
	v_add_f32_e32 v16, v27, v16
	v_add_f32_e32 v16, v134, v16
	v_add_f32_e32 v16, v135, v16
	v_add_f32_e32 v16, v136, v16
	v_add_f32_e32 v16, v137, v16
	ds_bpermute_b32 v17, v213, v16
	global_load_dwordx4 v[64:67], v168, s[38:39] offset:128
	global_load_dwordx4 v[28:31], v168, s[38:39] offset:160
	global_load_dwordx4 v[72:75], v168, s[38:39] offset:192
	global_load_dwordx4 v[68:71], v168, s[38:39] offset:224
	v_lshlrev_b32_e32 v18, 11, v139
	v_and_b32_e32 v18, 0xf800, v18
	s_waitcnt lgkmcnt(0)
	v_add_f32_e32 v16, v16, v17
	v_fmamk_f32 v16, v16, 0x3c000000, v216
	v_mul_f32_e32 v17, 0x4b800000, v16
	v_cmp_gt_f32_e32 vcc, s23, v16
	v_lshl_or_b32 v110, v141, 3, v18
	v_mbcnt_lo_u32_b32 v250, -1, 0
	v_mbcnt_hi_u32_b32 v250, -1, v250
	v_and_b32_e32 v251, 16, v250
	v_mul_u32_u24_e32 v251, 0x7fe, v251
	v_and_b32_e32 v250, 32, v250
	v_lshrrev_b32_e32 v250, 2, v250
	v_add_u32_e32 v110, v110, v250
	v_sub_u32_e32 v110, v110, v251
	v_add_u32_e32 v251, 0x8000, v110
	global_load_dwordx4 v[32:35], v168, s[38:39] offset:256
	global_load_dwordx4 v[18:21], v168, s[38:39] offset:288
	v_cndmask_b32_e32 v16, v16, v17, vcc
	v_rsq_f32_e32 v16, v16
	global_load_dwordx4 v[22:25], v168, s[38:39] offset:320
	global_load_dwordx4 v[52:55], v168, s[38:39] offset:352
	global_load_dwordx4 v[56:59], v168, s[38:39] offset:384
	global_load_dwordx4 v[60:63], v168, s[38:39] offset:416
	v_mul_f32_e32 v17, 0x45800000, v16
	v_cndmask_b32_e32 v16, v16, v17, vcc
	v_mul_f32_e32 v16, 0x3f4ccccd, v16
	v_pk_mul_f32 v[26:27], v[112:113], v[16:17] op_sel_hi:[1,0]
	v_pk_mul_f32 v[92:93], v[132:133], v[16:17] op_sel_hi:[1,0]
	s_waitcnt vmcnt(0)
; DI unsigned pk2(float lo, float hi) { bf2_t v = __builtin_convertvector((f32x2){lo, hi}, bf2_t); return __builtin_bit_cast(unsigned, v); }
; DI void dattn_unit2(const bf16_t* __restrict__ Qg, const bf16_t* __restrict__ Kg, const bf16_t* __restrict__ Vg, bf16_t* __restrict__ Og,
;                     int ntiles, int wave_tiles, float lam, const float* __restrict__ gsub, lds_t* shm) {
;     ...
; #pragma unroll
;   for (int c = 0; c < NC; ++c)
; #pragma unroll
;     for (int g4 = 0; g4 < 4; ++g4) {
;       const int dv0 = 32 * c + 8 * g4; f32x4 o;
; #pragma unroll
;       for (int e = 0; e < 4; ++e) o[e] = O[0][c][4 * g4 + e] * inv;
;       o = o * gld<f32x4>(gsub + dv0, 16u * h_f);
;       u32x2 w; w.x = pk2(o[0], o[1]); w.y = pk2(o[2], o[3]);
;       gst<u32x2>(Og + dv0, ooff, w);
;     }
	v_pk_mul_f32 v[26:27], v[100:101], v[26:27]
	v_pk_mul_f32 v[92:93], v[102:103], v[92:93]
	v_cvt_pk_bf16_f32 v218, v26, v27
	v_cvt_pk_bf16_f32 v219, v92, v93
	v_pk_mul_f32 v[26:27], v[114:115], v[16:17] op_sel_hi:[1,0]
	v_pk_mul_f32 v[92:93], v[118:119], v[16:17] op_sel_hi:[1,0]
	v_pk_mul_f32 v[26:27], v[96:97], v[26:27]
	v_pk_mul_f32 v[92:93], v[98:99], v[92:93]
	v_cvt_pk_bf16_f32 v220, v26, v27
	v_cvt_pk_bf16_f32 v221, v92, v93
	s_nop 1
	v_permlane32_swap_b32_e32 v218, v220
	v_permlane32_swap_b32_e32 v219, v221
	v_pk_mul_f32 v[26:27], v[116:117], v[16:17] op_sel_hi:[1,0]
	v_pk_mul_f32 v[92:93], v[122:123], v[16:17] op_sel_hi:[1,0]
	v_pk_mul_f32 v[26:27], v[104:105], v[26:27]
	v_pk_mul_f32 v[92:93], v[106:107], v[92:93]
	v_cvt_pk_bf16_f32 v222, v26, v27
	v_cvt_pk_bf16_f32 v223, v92, v93
	v_pk_mul_f32 v[26:27], v[120:121], v[16:17] op_sel_hi:[1,0]
	global_load_dwordx4 v[92:95], v168, s[38:39] offset:448
	v_pk_mul_f32 v[96:97], v[108:109], v[16:17] op_sel_hi:[1,0]
	v_pk_mul_f32 v[12:13], v[12:13], v[26:27]
	v_pk_mul_f32 v[14:15], v[14:15], v[96:97]
	v_cvt_pk_bf16_f32 v224, v12, v13
	v_cvt_pk_bf16_f32 v225, v14, v15
	s_nop 1
	v_permlane32_swap_b32_e32 v222, v224
	v_permlane32_swap_b32_e32 v223, v225
	s_nop 1
	v_permlane16_swap_b32_e32 v218, v222
	v_permlane16_swap_b32_e32 v219, v223
	v_permlane16_swap_b32_e32 v220, v224
	v_permlane16_swap_b32_e32 v221, v225
	global_store_dwordx4 v110, v[218:221], s[4:5]
	global_store_dwordx4 v251, v[222:225], s[4:5]
	global_load_dwordx4 v[12:15], v168, s[38:39] offset:480
	v_pk_mul_f32 v[26:27], v[80:81], v[16:17] op_sel_hi:[1,0]
	v_pk_mul_f32 v[80:81], v[82:83], v[16:17] op_sel_hi:[1,0]
	v_pk_mul_f32 v[0:1], v[0:1], v[16:17] op_sel_hi:[1,0]
	v_pk_mul_f32 v[2:3], v[2:3], v[16:17] op_sel_hi:[1,0]
	s_andn2_b64 vcc, exec, s[40:41]
	v_pk_mul_f32 v[66:67], v[66:67], v[80:81]
	v_pk_mul_f32 v[26:27], v[64:65], v[26:27]
	v_pk_mul_f32 v[64:65], v[86:87], v[16:17] op_sel_hi:[1,0]
	v_cvt_pk_bf16_f32 v226, v26, v27
	v_cvt_pk_bf16_f32 v227, v66, v67
	v_pk_mul_f32 v[26:27], v[84:85], v[16:17] op_sel_hi:[1,0]
	v_pk_mul_f32 v[30:31], v[30:31], v[64:65]
	v_pk_mul_f32 v[26:27], v[28:29], v[26:27]
	v_pk_mul_f32 v[28:29], v[90:91], v[16:17] op_sel_hi:[1,0]
	v_cvt_pk_bf16_f32 v228, v26, v27
	v_cvt_pk_bf16_f32 v229, v30, v31
	s_nop 1
	v_permlane32_swap_b32_e32 v226, v228
	v_permlane32_swap_b32_e32 v227, v229
	v_pk_mul_f32 v[26:27], v[88:89], v[16:17] op_sel_hi:[1,0]
	v_pk_mul_f32 v[28:29], v[74:75], v[28:29]
	v_pk_mul_f32 v[26:27], v[72:73], v[26:27]
	v_pk_mul_f32 v[2:3], v[58:59], v[2:3]
	v_cvt_pk_bf16_f32 v230, v26, v27
	v_cvt_pk_bf16_f32 v231, v28, v29
	v_pk_mul_f32 v[26:27], v[76:77], v[16:17] op_sel_hi:[1,0]
	v_pk_mul_f32 v[28:29], v[78:79], v[16:17] op_sel_hi:[1,0]
	v_pk_mul_f32 v[26:27], v[68:69], v[26:27]
	v_pk_mul_f32 v[28:29], v[70:71], v[28:29]
	v_cvt_pk_bf16_f32 v232, v26, v27
	v_cvt_pk_bf16_f32 v233, v28, v29
	s_nop 1
	v_permlane32_swap_b32_e32 v230, v232
	v_permlane32_swap_b32_e32 v231, v233
	s_nop 1
	v_permlane16_swap_b32_e32 v226, v230
	v_permlane16_swap_b32_e32 v227, v231
	v_permlane16_swap_b32_e32 v228, v232
	v_permlane16_swap_b32_e32 v229, v233
	global_store_dwordx4 v110, v[226:229], s[4:5] offset:64
	global_store_dwordx4 v251, v[230:233], s[4:5] offset:64
	v_pk_mul_f32 v[26:27], v[48:49], v[16:17] op_sel_hi:[1,0]
	v_pk_mul_f32 v[28:29], v[50:51], v[16:17] op_sel_hi:[1,0]
	v_pk_mul_f32 v[26:27], v[32:33], v[26:27]
	v_pk_mul_f32 v[28:29], v[34:35], v[28:29]
	v_pk_mul_f32 v[0:1], v[56:57], v[0:1]
	v_cvt_pk_bf16_f32 v234, v26, v27
	v_cvt_pk_bf16_f32 v235, v28, v29
	v_cvt_pk_bf16_f32 v242, v0, v1
	v_cvt_pk_bf16_f32 v243, v2, v3
	v_pk_mul_f32 v[26:27], v[36:37], v[16:17] op_sel_hi:[1,0]
	v_pk_mul_f32 v[28:29], v[38:39], v[16:17] op_sel_hi:[1,0]
	v_pk_mul_f32 v[0:1], v[4:5], v[16:17] op_sel_hi:[1,0]
	v_pk_mul_f32 v[2:3], v[6:7], v[16:17] op_sel_hi:[1,0]
	v_pk_mul_f32 v[20:21], v[20:21], v[28:29]
	v_pk_mul_f32 v[18:19], v[18:19], v[26:27]
	v_pk_mul_f32 v[2:3], v[62:63], v[2:3]
	v_pk_mul_f32 v[0:1], v[60:61], v[0:1]
	v_cvt_pk_bf16_f32 v236, v18, v19
	v_cvt_pk_bf16_f32 v237, v20, v21
	v_cvt_pk_bf16_f32 v244, v0, v1
	v_cvt_pk_bf16_f32 v245, v2, v3
	s_nop 1
	v_permlane32_swap_b32_e32 v234, v236
	v_permlane32_swap_b32_e32 v235, v237
	v_pk_mul_f32 v[18:19], v[40:41], v[16:17] op_sel_hi:[1,0]
	v_pk_mul_f32 v[20:21], v[42:43], v[16:17] op_sel_hi:[1,0]
	s_nop 1
	v_permlane32_swap_b32_e32 v242, v244
	v_permlane32_swap_b32_e32 v243, v245
	v_pk_mul_f32 v[0:1], v[8:9], v[16:17] op_sel_hi:[1,0]
	v_pk_mul_f32 v[2:3], v[10:11], v[16:17] op_sel_hi:[1,0]
	v_pk_mul_f32 v[20:21], v[24:25], v[20:21]
	v_pk_mul_f32 v[18:19], v[22:23], v[18:19]
	s_waitcnt vmcnt(5)
	v_pk_mul_f32 v[2:3], v[94:95], v[2:3]
	v_pk_mul_f32 v[0:1], v[92:93], v[0:1]
	v_cvt_pk_bf16_f32 v238, v18, v19
	v_cvt_pk_bf16_f32 v239, v20, v21
	v_cvt_pk_bf16_f32 v246, v0, v1
	v_cvt_pk_bf16_f32 v247, v2, v3
	v_pk_mul_f32 v[18:19], v[44:45], v[16:17] op_sel_hi:[1,0]
	v_pk_mul_f32 v[20:21], v[46:47], v[16:17] op_sel_hi:[1,0]
	v_pk_mul_f32 v[0:1], v[128:129], v[16:17] op_sel_hi:[1,0]
	v_pk_mul_f32 v[2:3], v[130:131], v[16:17] op_sel_hi:[1,0]
	v_pk_mul_f32 v[20:21], v[54:55], v[20:21]
	v_pk_mul_f32 v[18:19], v[52:53], v[18:19]
	s_waitcnt vmcnt(2)
	v_pk_mul_f32 v[2:3], v[14:15], v[2:3]
	v_pk_mul_f32 v[0:1], v[12:13], v[0:1]
	v_cvt_pk_bf16_f32 v240, v18, v19
	v_cvt_pk_bf16_f32 v241, v20, v21
	v_cvt_pk_bf16_f32 v248, v0, v1
	v_cvt_pk_bf16_f32 v249, v2, v3
	s_nop 1
	v_permlane32_swap_b32_e32 v238, v240
	v_permlane32_swap_b32_e32 v239, v241
	s_nop 1
	v_permlane16_swap_b32_e32 v234, v238
	v_permlane16_swap_b32_e32 v235, v239
	v_permlane16_swap_b32_e32 v236, v240
	v_permlane16_swap_b32_e32 v237, v241
	global_store_dwordx4 v110, v[234:237], s[4:5] offset:128
	global_store_dwordx4 v251, v[238:241], s[4:5] offset:128
	s_nop 1
	v_permlane32_swap_b32_e32 v246, v248
	v_permlane32_swap_b32_e32 v247, v249
	s_nop 1
	v_permlane16_swap_b32_e32 v242, v246
	v_permlane16_swap_b32_e32 v243, v247
	v_permlane16_swap_b32_e32 v244, v248
	v_permlane16_swap_b32_e32 v245, v249
	global_store_dwordx4 v110, v[242:245], s[4:5] offset:192
	global_store_dwordx4 v251, v[246:249], s[4:5] offset:192
	s_mov_b64 s[4:5], 0
	s_cbranch_vccz .LBB0_406
